# the three GEMM K-loop heads padded to 64-byte boundaries
# baseline (speedup 1.0000x reference)
.LBB0_233:
	v_mov_b64_e32 v[0:1], 0x5a0
	s_ashr_i32 s95, s94, 31
	v_cmp_lt_i64_e32 vcc, s[34:35], v[0:1]
	s_lshl_b64 s[34:35], s[94:95], 20
	s_add_u32 s96, s56, s34
	s_addc_u32 s97, s57, s35
	s_and_b64 s[34:35], vcc, exec
	s_cselect_b32 s9, s97, s11
	s_cselect_b32 s89, s96, s10
	s_ashr_i32 s71, s70, 31
	s_lshl_b64 s[34:35], s[70:71], 20
	s_add_u32 s98, s82, s34
	s_addc_u32 s99, s83, s35
	s_and_b64 s[34:35], vcc, exec
	s_cselect_b32 s71, s99, s29
	s_cselect_b32 s91, s98, s28
	s_add_u32 s10, s10, 0x80080
	s_addc_u32 s11, s11, 0
	s_add_u32 s93, s28, 0x100
	v_mov_b32_e32 v0, 0
	s_addc_u32 s95, s29, 0
	s_mov_b32 vcc_lo, -2
	v_mov_b32_e32 v1, v0
	v_mov_b32_e32 v2, v0
	v_mov_b32_e32 v3, v0
	v_mov_b32_e32 v8, v0
	v_mov_b32_e32 v9, v0
	v_mov_b32_e32 v10, v0
	v_mov_b32_e32 v11, v0
	v_mov_b32_e32 v16, v0
	v_mov_b32_e32 v17, v0
	v_mov_b32_e32 v18, v0
	v_mov_b32_e32 v19, v0
	v_mov_b32_e32 v24, v0
	v_mov_b32_e32 v25, v0
	v_mov_b32_e32 v26, v0
	v_mov_b32_e32 v27, v0
	v_mov_b32_e32 v32, v0
	v_mov_b32_e32 v33, v0
	v_mov_b32_e32 v34, v0
	v_mov_b32_e32 v35, v0
	v_mov_b32_e32 v40, v0
	v_mov_b32_e32 v41, v0
	v_mov_b32_e32 v42, v0
	v_mov_b32_e32 v43, v0
	v_mov_b32_e32 v48, v0
	v_mov_b32_e32 v49, v0
	v_mov_b32_e32 v50, v0
	v_mov_b32_e32 v51, v0
	v_mov_b32_e32 v56, v0
	v_mov_b32_e32 v57, v0
	v_mov_b32_e32 v58, v0
	v_mov_b32_e32 v59, v0
	v_mov_b32_e32 v4, v0
	v_mov_b32_e32 v5, v0
	v_mov_b32_e32 v6, v0
	v_mov_b32_e32 v7, v0
	v_mov_b32_e32 v12, v0
	v_mov_b32_e32 v13, v0
	v_mov_b32_e32 v14, v0
	v_mov_b32_e32 v15, v0
	v_mov_b32_e32 v20, v0
	v_mov_b32_e32 v21, v0
	v_mov_b32_e32 v22, v0
	v_mov_b32_e32 v23, v0
	v_mov_b32_e32 v28, v0
	v_mov_b32_e32 v29, v0
	v_mov_b32_e32 v30, v0
	v_mov_b32_e32 v31, v0
	v_mov_b32_e32 v36, v0
	v_mov_b32_e32 v37, v0
	v_mov_b32_e32 v38, v0
	v_mov_b32_e32 v39, v0
	v_mov_b32_e32 v44, v0
	v_mov_b32_e32 v45, v0
	v_mov_b32_e32 v46, v0
	v_mov_b32_e32 v47, v0
	v_mov_b32_e32 v52, v0
	v_mov_b32_e32 v53, v0
	v_mov_b32_e32 v54, v0
	v_mov_b32_e32 v55, v0
	v_mov_b32_e32 v60, v0
	v_mov_b32_e32 v61, v0
	v_mov_b32_e32 v62, v0
	v_mov_b32_e32 v63, v0
	v_mov_b32_e32 v64, v0
	v_mov_b32_e32 v65, v0
	v_mov_b32_e32 v66, v0
	v_mov_b32_e32 v67, v0
	v_mov_b32_e32 v72, v0
	v_mov_b32_e32 v73, v0
	v_mov_b32_e32 v74, v0
	v_mov_b32_e32 v75, v0
	v_mov_b32_e32 v80, v0
	v_mov_b32_e32 v81, v0
	v_mov_b32_e32 v82, v0
	v_mov_b32_e32 v83, v0
	v_mov_b32_e32 v88, v0
	v_mov_b32_e32 v89, v0
	v_mov_b32_e32 v90, v0
	v_mov_b32_e32 v91, v0
	v_mov_b32_e32 v96, v0
	v_mov_b32_e32 v97, v0
	v_mov_b32_e32 v98, v0
	v_mov_b32_e32 v99, v0
	v_mov_b32_e32 v104, v0
	v_mov_b32_e32 v105, v0
	v_mov_b32_e32 v106, v0
	v_mov_b32_e32 v107, v0
	v_mov_b32_e32 v112, v0
	v_mov_b32_e32 v113, v0
	v_mov_b32_e32 v114, v0
	v_mov_b32_e32 v115, v0
	v_mov_b32_e32 v120, v0
	v_mov_b32_e32 v121, v0
	v_mov_b32_e32 v122, v0
	v_mov_b32_e32 v123, v0
	v_mov_b32_e32 v68, v0
	v_mov_b32_e32 v69, v0
	v_mov_b32_e32 v70, v0
	v_mov_b32_e32 v71, v0
	v_mov_b32_e32 v76, v0
	v_mov_b32_e32 v77, v0
	v_mov_b32_e32 v78, v0
	v_mov_b32_e32 v79, v0
	v_mov_b32_e32 v84, v0
	v_mov_b32_e32 v85, v0
	v_mov_b32_e32 v86, v0
	v_mov_b32_e32 v87, v0
	v_mov_b32_e32 v92, v0
	v_mov_b32_e32 v93, v0
	v_mov_b32_e32 v94, v0
	v_mov_b32_e32 v95, v0
	v_mov_b32_e32 v100, v0
	v_mov_b32_e32 v101, v0
	v_mov_b32_e32 v102, v0
	v_mov_b32_e32 v103, v0
	v_mov_b32_e32 v108, v0
	v_mov_b32_e32 v109, v0
	v_mov_b32_e32 v110, v0
	v_mov_b32_e32 v111, v0
	v_mov_b32_e32 v116, v0
	v_mov_b32_e32 v117, v0
	v_mov_b32_e32 v118, v0
	v_mov_b32_e32 v119, v0
	v_mov_b32_e32 v124, v0
	v_mov_b32_e32 v125, v0
	v_mov_b32_e32 v126, v0
	v_mov_b32_e32 v127, v0
	s_nop 0
	s_nop 0
	s_nop 0
	s_nop 0
	s_nop 0
	s_nop 0
	s_nop 0
	s_nop 0
	s_nop 0
	s_nop 0

.LBB0_557:
	s_ashr_i32 s41, s40, 31
	s_xor_b64 s[44:45], s[34:35], -1
	s_lshl_b64 s[46:47], s[40:41], 20
	s_add_u32 s3, s8, s46
	s_addc_u32 s39, s9, s47
	s_ashr_i32 s43, s42, 31
	s_lshl_b64 s[48:49], s[42:43], 1
	s_add_u32 s46, s3, s48
	s_addc_u32 s47, s39, s49
	s_and_b64 s[50:51], s[34:35], exec
	s_cselect_b32 s41, s47, s11
	s_cselect_b32 s43, s46, s10
	s_ashr_i32 s39, s38, 31
	s_lshl_b64 s[50:51], s[38:39], 20
	s_add_u32 s3, s72, s50
	s_addc_u32 s39, s73, s51
	s_add_u32 s48, s3, s48
	s_addc_u32 s49, s39, s49
	s_and_b64 s[34:35], s[34:35], exec
	s_cselect_b32 s39, s49, s29
	s_cselect_b32 s50, s48, s28
	s_add_u32 s10, s10, 0x80080
	s_addc_u32 s11, s11, 0
	s_add_u32 s51, s28, 0x100
	v_mov_b32_e32 v0, 0
	s_addc_u32 s85, s29, 0
	s_mov_b32 s86, 2
	v_mov_b32_e32 v1, v0
	v_mov_b32_e32 v2, v0
	v_mov_b32_e32 v3, v0
	v_mov_b32_e32 v4, v0
	v_mov_b32_e32 v5, v0
	v_mov_b32_e32 v6, v0
	v_mov_b32_e32 v7, v0
	v_mov_b32_e32 v16, v0
	v_mov_b32_e32 v17, v0
	v_mov_b32_e32 v18, v0
	v_mov_b32_e32 v19, v0
	v_mov_b32_e32 v20, v0
	v_mov_b32_e32 v21, v0
	v_mov_b32_e32 v22, v0
	v_mov_b32_e32 v23, v0
	v_mov_b32_e32 v32, v0
	v_mov_b32_e32 v33, v0
	v_mov_b32_e32 v34, v0
	v_mov_b32_e32 v35, v0
	v_mov_b32_e32 v36, v0
	v_mov_b32_e32 v37, v0
	v_mov_b32_e32 v38, v0
	v_mov_b32_e32 v39, v0
	v_mov_b32_e32 v64, v0
	v_mov_b32_e32 v65, v0
	v_mov_b32_e32 v66, v0
	v_mov_b32_e32 v67, v0
	v_mov_b32_e32 v68, v0
	v_mov_b32_e32 v69, v0
	v_mov_b32_e32 v70, v0
	v_mov_b32_e32 v71, v0
	v_mov_b32_e32 v8, v0
	v_mov_b32_e32 v9, v0
	v_mov_b32_e32 v10, v0
	v_mov_b32_e32 v11, v0
	v_mov_b32_e32 v12, v0
	v_mov_b32_e32 v13, v0
	v_mov_b32_e32 v14, v0
	v_mov_b32_e32 v15, v0
	v_mov_b32_e32 v24, v0
	v_mov_b32_e32 v25, v0
	v_mov_b32_e32 v26, v0
	v_mov_b32_e32 v27, v0
	v_mov_b32_e32 v28, v0
	v_mov_b32_e32 v29, v0
	v_mov_b32_e32 v30, v0
	v_mov_b32_e32 v31, v0
	v_mov_b32_e32 v48, v0
	v_mov_b32_e32 v49, v0
	v_mov_b32_e32 v50, v0
	v_mov_b32_e32 v51, v0
	v_mov_b32_e32 v56, v0
	v_mov_b32_e32 v57, v0
	v_mov_b32_e32 v58, v0
	v_mov_b32_e32 v59, v0
	v_mov_b32_e32 v72, v0
	v_mov_b32_e32 v73, v0
	v_mov_b32_e32 v74, v0
	v_mov_b32_e32 v75, v0
	v_mov_b32_e32 v76, v0
	v_mov_b32_e32 v77, v0
	v_mov_b32_e32 v78, v0
	v_mov_b32_e32 v79, v0
	v_mov_b32_e32 v80, v0
	v_mov_b32_e32 v81, v0
	v_mov_b32_e32 v82, v0
	v_mov_b32_e32 v83, v0
	v_mov_b32_e32 v84, v0
	v_mov_b32_e32 v85, v0
	v_mov_b32_e32 v86, v0
	v_mov_b32_e32 v87, v0
	v_mov_b32_e32 v96, v0
	v_mov_b32_e32 v97, v0
	v_mov_b32_e32 v98, v0
	v_mov_b32_e32 v99, v0
	v_mov_b32_e32 v100, v0
	v_mov_b32_e32 v101, v0
	v_mov_b32_e32 v102, v0
	v_mov_b32_e32 v103, v0
	v_mov_b32_e32 v112, v0
	v_mov_b32_e32 v113, v0
	v_mov_b32_e32 v114, v0
	v_mov_b32_e32 v115, v0
	v_mov_b32_e32 v116, v0
	v_mov_b32_e32 v117, v0
	v_mov_b32_e32 v118, v0
	v_mov_b32_e32 v119, v0
	v_mov_b32_e32 v128, v0
	v_mov_b32_e32 v129, v0
	v_mov_b32_e32 v130, v0
	v_mov_b32_e32 v131, v0
	v_mov_b32_e32 v132, v0
	v_mov_b32_e32 v133, v0
	v_mov_b32_e32 v134, v0
	v_mov_b32_e32 v135, v0
	v_mov_b32_e32 v88, v0
	v_mov_b32_e32 v89, v0
	v_mov_b32_e32 v90, v0
	v_mov_b32_e32 v91, v0
	v_mov_b32_e32 v92, v0
	v_mov_b32_e32 v93, v0
	v_mov_b32_e32 v94, v0
	v_mov_b32_e32 v95, v0
	v_mov_b32_e32 v104, v0
	v_mov_b32_e32 v105, v0
	v_mov_b32_e32 v106, v0
	v_mov_b32_e32 v107, v0
	v_mov_b32_e32 v108, v0
	v_mov_b32_e32 v109, v0
	v_mov_b32_e32 v110, v0
	v_mov_b32_e32 v111, v0
	v_mov_b32_e32 v120, v0
	v_mov_b32_e32 v121, v0
	v_mov_b32_e32 v122, v0
	v_mov_b32_e32 v123, v0
	v_mov_b32_e32 v124, v0
	v_mov_b32_e32 v125, v0
	v_mov_b32_e32 v126, v0
	v_mov_b32_e32 v127, v0
	v_mov_b32_e32 v136, v0
	v_mov_b32_e32 v137, v0
	v_mov_b32_e32 v138, v0
	v_mov_b32_e32 v139, v0
	v_mov_b32_e32 v140, v0
	v_mov_b32_e32 v141, v0
	v_mov_b32_e32 v142, v0
	v_mov_b32_e32 v143, v0
	s_nop 0
	s_nop 0
	s_nop 0
	s_nop 0
	s_nop 0
	s_nop 0
	s_nop 0
	s_nop 0
	s_nop 0

.LBB0_639:
	s_mov_b64 s[34:35], s[8:9]
	s_add_u32 s83, s34, 0x100
	s_addc_u32 s84, s35, 0
	v_add_co_u32_e64 v56, s[26:27], s80, 1
	s_and_b64 s[8:9], s[26:27], exec
	s_cselect_b32 s10, s4, s69
	s_cselect_b32 s82, s66, 0
	s_cmp_gt_i32 s80, 0
	s_cselect_b64 s[20:21], -1, 0
	s_ashr_i32 s11, s10, 31
	s_lshl_b64 s[8:9], s[10:11], 21
	s_add_u32 s3, s56, s8
	s_addc_u32 s8, s57, s9
	s_lshl_b32 s9, s82, 1
	s_add_u32 s24, s3, s9
	s_addc_u32 s25, s8, 0
	s_add_u32 s8, s42, s9
	s_addc_u32 s9, s43, 0
	s_cmp_lt_i32 s80, 1
	s_cselect_b64 s[28:29], -1, 0
	s_and_b64 s[36:37], s[28:29], exec
	s_cselect_b32 s11, s25, s23
	s_cselect_b32 s85, s24, s22
	s_cselect_b32 s86, s9, s35
	s_cselect_b32 s87, s8, s34
	s_lshl_b32 s3, s49, 7
	s_addk_i32 s3, 0xfc00
	v_readfirstlane_b32 s81, v56
	v_lshl_add_u64 v[58:59], s[22:23], 0, v[142:143]
	v_lshl_add_u64 v[146:147], s[22:23], 0, v[144:145]
	s_add_u32 s88, s3, 0x300
	s_mov_b64 s[34:35], 0
	s_mov_b32 s89, 0
	s_nop 0
	s_nop 0
	s_nop 0
	s_nop 0
